# baseline (speedup 1.0000x reference)
.LBB0_406:
	v_mov_b32_e32 v206, v218
	s_add_i32 s22, s19, s37
	v_ashrrev_i32_e32 v220, 3, v206
	v_add_u32_e32 v134, s22, v220
	s_lshl_b64 s[22:23], s[20:21], 1
	v_and_b32_e32 v221, 7, v206
	s_add_u32 s22, s40, s22
	s_addc_u32 s23, s41, s23
	v_lshlrev_b32_e32 v136, 3, v221
	v_mov_b32_e32 v137, v0
	v_ashrrev_i32_e32 v135, 31, v134
	v_lshl_add_u64 v[138:139], s[22:23], 0, v[136:137]
	v_lshlrev_b64 v[224:225], 11, v[134:135]
	v_lshl_add_u64 v[136:137], v[138:139], 0, v[224:225]
	v_add_co_u32_e32 v140, vcc, s81, v136
	v_ashrrev_i32_e32 v214, 2, v206
	s_nop 0
	v_addc_co_u32_e32 v141, vcc, 0, v137, vcc
	global_load_dwordx2 v[212:213], v[136:137], off
	global_load_dwordx2 v[226:227], v[140:141], off
	global_load_dwordx2 v[228:229], v[140:141], off offset:256
	global_load_dwordx2 v[230:231], v[136:137], off offset:256
	v_add_u32_e32 v136, 16, v134
	v_ashrrev_i32_e32 v137, 31, v136
	v_lshlrev_b64 v[198:199], 11, v[136:137]
	v_lshl_add_u64 v[136:137], v[138:139], 0, v[198:199]
	v_add_co_u32_e32 v140, vcc, s81, v136
	v_lshlrev_b32_e32 v215, 4, v221
	s_nop 0
	v_addc_co_u32_e32 v141, vcc, 0, v137, vcc
	global_load_dwordx2 v[204:205], v[136:137], off
	global_load_dwordx2 v[202:203], v[140:141], off
	global_load_dwordx2 v[196:197], v[140:141], off offset:256
	global_load_dwordx2 v[200:201], v[136:137], off offset:256
	v_add_u32_e32 v136, 32, v134
	v_ashrrev_i32_e32 v137, 31, v136
	v_lshlrev_b64 v[188:189], 11, v[136:137]
	v_lshl_add_u64 v[136:137], v[138:139], 0, v[188:189]
	v_add_co_u32_e32 v140, vcc, s81, v136
	v_mov_b32_e32 v233, s21
	s_nop 0
	v_addc_co_u32_e32 v141, vcc, 0, v137, vcc
	global_load_dwordx2 v[194:195], v[136:137], off
	global_load_dwordx2 v[192:193], v[140:141], off
	global_load_dwordx2 v[186:187], v[140:141], off offset:256
	global_load_dwordx2 v[190:191], v[136:137], off offset:256
	v_add_u32_e32 v136, 48, v134
	v_ashrrev_i32_e32 v137, 31, v136
	v_lshlrev_b64 v[178:179], 11, v[136:137]
	v_lshl_add_u64 v[136:137], v[138:139], 0, v[178:179]
	v_add_co_u32_e32 v140, vcc, s81, v136
	v_mul_f32_e32 v122, s33, v122
	s_nop 0
	v_addc_co_u32_e32 v141, vcc, 0, v137, vcc
	global_load_dwordx2 v[184:185], v[136:137], off
	global_load_dwordx2 v[182:183], v[140:141], off
	global_load_dwordx2 v[176:177], v[140:141], off offset:256
	global_load_dwordx2 v[180:181], v[136:137], off offset:256
	v_add_u32_e32 v136, 0x80, v134
	v_ashrrev_i32_e32 v137, 31, v136
	v_lshlrev_b64 v[168:169], 11, v[136:137]
	v_lshl_add_u64 v[136:137], v[138:139], 0, v[168:169]
	v_add_co_u32_e32 v140, vcc, s81, v136
	v_mul_f32_e32 v114, s33, v114
	s_nop 0
	v_addc_co_u32_e32 v141, vcc, 0, v137, vcc
	global_load_dwordx2 v[174:175], v[136:137], off
	global_load_dwordx2 v[172:173], v[140:141], off
	global_load_dwordx2 v[166:167], v[140:141], off offset:256
	global_load_dwordx2 v[170:171], v[136:137], off offset:256
	v_add_u32_e32 v136, 0x90, v134
	v_ashrrev_i32_e32 v137, 31, v136
	v_lshlrev_b64 v[158:159], 11, v[136:137]
	v_lshl_add_u64 v[136:137], v[138:139], 0, v[158:159]
	v_add_co_u32_e32 v140, vcc, s81, v136
	v_mul_f32_e32 v106, s33, v106
	s_nop 0
	v_addc_co_u32_e32 v141, vcc, 0, v137, vcc
	global_load_dwordx2 v[164:165], v[136:137], off
	global_load_dwordx2 v[162:163], v[140:141], off
	global_load_dwordx2 v[156:157], v[140:141], off offset:256
	global_load_dwordx2 v[160:161], v[136:137], off offset:256
	v_add_u32_e32 v136, 0xa0, v134
	v_ashrrev_i32_e32 v137, 31, v136
	v_lshlrev_b64 v[148:149], 11, v[136:137]
	v_lshl_add_u64 v[136:137], v[138:139], 0, v[148:149]
	v_add_u32_e32 v134, 0xb0, v134
	v_add_co_u32_e32 v140, vcc, s81, v136
	v_ashrrev_i32_e32 v135, 31, v134
	s_nop 0
	v_addc_co_u32_e32 v141, vcc, 0, v137, vcc
	global_load_dwordx2 v[154:155], v[136:137], off
	global_load_dwordx2 v[152:153], v[140:141], off
	global_load_dwordx2 v[146:147], v[140:141], off offset:256
	global_load_dwordx2 v[150:151], v[136:137], off offset:256
	v_lshlrev_b64 v[136:137], 11, v[134:135]
	v_lshl_add_u64 v[138:139], v[138:139], 0, v[136:137]
	v_and_b32_e32 v140, 15, v206
	v_lshl_or_b32 v141, v221, 2, s38
	v_add_co_u32_e32 v134, vcc, s81, v138
	v_or_b32_e32 v232, s20, v141
	v_and_b32_e32 v141, 0xffffffc, v214
	v_lshl_add_u32 v206, v140, 2, s35
	v_mul_lo_u32 v140, v220, s94
	v_addc_co_u32_e32 v135, vcc, 0, v139, vcc
	v_add3_u32 v222, s35, v140, v215
	v_mad_u64_u32 v[140:141], s[20:21], v141, s94, v[206:207]
	global_load_dwordx2 v[144:145], v[138:139], off
	global_load_dwordx2 v[142:143], v[134:135], off
	s_nop 0
	global_load_dwordx2 v[134:135], v[134:135], off offset:256
	s_nop 0
	global_load_dwordx2 v[138:139], v[138:139], off offset:256
	ds_write_b32 v140, v122
	v_mul_f32_e32 v122, s33, v126
	ds_write_b32 v140, v122 offset:64
	v_mul_f32_e32 v122, s33, v123
	ds_write_b32 v140, v122 offset:144
	v_mul_f32_e32 v122, s33, v127
	ds_write_b32 v140, v122 offset:208
	v_mul_f32_e32 v122, s33, v124
	ds_write_b32 v140, v122 offset:288
	v_mul_f32_e32 v122, s33, v128
	ds_write_b32 v140, v122 offset:352
	v_or_b32_e32 v122, 3, v214
	v_mad_u64_u32 v[126:127], s[20:21], v122, s94, v[206:207]
	v_mul_f32_e32 v122, s33, v125
	ds_write_b32 v126, v122
	v_mul_f32_e32 v122, s33, v129
	ds_write_b32 v126, v122 offset:64
	s_waitcnt vmcnt(0)
	v_lshlrev_b32_e32 v234, 16, v212
	v_and_b32_e32 v235, 0xffff0000, v212
	v_lshlrev_b32_e32 v236, 16, v213
	v_and_b32_e32 v237, 0xffff0000, v213
	ds_read_b128 v[122:125], v222
	ds_read_b128 v[212:215], v222 offset:1152
	ds_write_b32 v140, v114
	v_mul_f32_e32 v114, s33, v118
	ds_write_b32 v140, v114 offset:64
	v_mul_f32_e32 v114, s33, v115
	ds_write_b32 v140, v114 offset:144
	v_mul_f32_e32 v114, s33, v119
	ds_write_b32 v140, v114 offset:208
	v_mul_f32_e32 v114, s33, v116
	ds_write_b32 v140, v114 offset:288
	v_mul_f32_e32 v114, s33, v120
	ds_write_b32 v140, v114 offset:352
	v_mul_f32_e32 v114, s33, v117
	v_lshlrev_b32_e32 v128, 16, v227
	v_and_b32_e32 v129, 0xffff0000, v227
	ds_write_b32 v126, v114
	v_mul_f32_e32 v114, s33, v121
	s_waitcnt lgkmcnt(8)
	v_pk_add_f32 v[234:235], v[122:123], v[234:235]
	s_waitcnt lgkmcnt(7)
	v_pk_add_f32 v[122:123], v[214:215], v[128:129]
	v_lshlrev_b64 v[128:129], 1, v[232:233]
	ds_write_b32 v126, v114 offset:64
	v_lshlrev_b32_e32 v238, 16, v226
	v_and_b32_e32 v239, 0xffff0000, v226
	v_lshl_add_u64 v[232:233], s[8:9], 0, v[128:129]
	ds_read_b128 v[114:117], v222
	ds_read_b128 v[118:121], v222 offset:1152
	v_pk_add_f32 v[226:227], v[124:125], v[236:237]
	v_pk_add_f32 v[124:125], v[212:213], v[238:239]
	v_cvt_pk_bf16_f32 v212, v234, v235
	v_lshl_add_u64 v[224:225], v[232:233], 0, v[224:225]
	v_mul_f32_e32 v127, v235, v235
	v_cvt_pk_bf16_f32 v213, v226, v227
	global_store_dwordx2 v[224:225], v[212:213], off
	v_add_co_u32_e32 v212, vcc, s81, v224
	v_fmac_f32_e32 v127, v234, v234
	v_cvt_pk_bf16_f32 v214, v124, v125
	v_cvt_pk_bf16_f32 v215, v122, v123
	s_nop 0
	v_addc_co_u32_e32 v213, vcc, 0, v225, vcc
	v_fmac_f32_e32 v127, v226, v226
	global_store_dwordx2 v[212:213], v[214:215], off
	v_fmac_f32_e32 v127, v227, v227
	v_lshlrev_b32_e32 v214, 16, v230
	v_and_b32_e32 v215, 0xffff0000, v230
	v_lshlrev_b32_e32 v226, 16, v231
	v_and_b32_e32 v227, 0xffff0000, v231
	v_lshlrev_b32_e32 v230, 16, v228
	v_and_b32_e32 v231, 0xffff0000, v228
	v_lshlrev_b32_e32 v228, 16, v229
	v_and_b32_e32 v229, 0xffff0000, v229
	s_waitcnt lgkmcnt(1)
	v_pk_add_f32 v[226:227], v[116:117], v[226:227]
	v_pk_add_f32 v[214:215], v[114:115], v[214:215]
	s_waitcnt lgkmcnt(0)
	v_pk_add_f32 v[116:117], v[118:119], v[230:231]
	v_cvt_pk_bf16_f32 v118, v214, v215
	v_cvt_pk_bf16_f32 v119, v226, v227
	v_pk_add_f32 v[114:115], v[120:121], v[228:229]
	v_cvt_pk_bf16_f32 v120, v116, v117
	v_mul_f32_e32 v98, s33, v98
	v_cvt_pk_bf16_f32 v121, v114, v115
	global_store_dwordx2 v[224:225], v[118:119], off offset:256
	global_store_dwordx2 v[212:213], v[120:121], off offset:256
	ds_write_b32 v140, v106
	v_mul_f32_e32 v106, s33, v110
	ds_write_b32 v140, v106 offset:64
	v_mul_f32_e32 v106, s33, v107
	ds_write_b32 v140, v106 offset:144
	v_mul_f32_e32 v106, s33, v111
	ds_write_b32 v140, v106 offset:208
	v_mul_f32_e32 v106, s33, v108
	ds_write_b32 v140, v106 offset:288
	v_mul_f32_e32 v106, s33, v112
	ds_write_b32 v140, v106 offset:352
	v_mul_f32_e32 v106, s33, v109
	ds_write_b32 v126, v106
	v_mul_f32_e32 v106, s33, v113
	v_mul_f32_e32 v118, v215, v215
	ds_write_b32 v126, v106 offset:64
	v_fmac_f32_e32 v118, v214, v214
	ds_read_b128 v[106:109], v222
	ds_read_b128 v[212:215], v222 offset:1152
	ds_write_b32 v140, v98
	v_mul_f32_e32 v98, s33, v102
	ds_write_b32 v140, v98 offset:64
	v_mul_f32_e32 v98, s33, v99
	ds_write_b32 v140, v98 offset:144
	v_mul_f32_e32 v98, s33, v103
	ds_write_b32 v140, v98 offset:208
	v_mul_f32_e32 v98, s33, v100
	v_lshlrev_b32_e32 v120, 16, v204
	v_and_b32_e32 v121, 0xffff0000, v204
	v_lshlrev_b32_e32 v204, 16, v205
	v_and_b32_e32 v205, 0xffff0000, v205
	v_lshl_add_u64 v[198:199], s[8:9], 0, v[198:199]
	ds_write_b32 v140, v98 offset:288
	v_mul_f32_e32 v98, s33, v104
	s_waitcnt lgkmcnt(6)
	v_pk_add_f32 v[110:111], v[108:109], v[204:205]
	v_pk_add_f32 v[112:113], v[106:107], v[120:121]
	v_lshl_add_u64 v[204:205], v[198:199], 0, v[128:129]
	v_cvt_pk_bf16_f32 v120, v112, v113
	ds_write_b32 v140, v98 offset:352
	v_mul_f32_e32 v98, s33, v101
	v_lshlrev_b32_e32 v224, 16, v202
	v_and_b32_e32 v225, 0xffff0000, v202
	v_lshlrev_b32_e32 v202, 16, v203
	v_and_b32_e32 v203, 0xffff0000, v203
	v_cvt_pk_bf16_f32 v121, v110, v111
	global_store_dwordx2 v[204:205], v[120:121], off
	v_add_co_u32_e32 v120, vcc, s81, v204
	ds_write_b32 v126, v98
	v_mul_f32_e32 v98, s33, v105
	s_waitcnt lgkmcnt(7)
	v_pk_add_f32 v[106:107], v[214:215], v[202:203]
	v_pk_add_f32 v[108:109], v[212:213], v[224:225]
	v_cvt_pk_bf16_f32 v203, v106, v107
	v_addc_co_u32_e32 v121, vcc, 0, v205, vcc
	v_cvt_pk_bf16_f32 v202, v108, v109
	ds_write_b32 v126, v98 offset:64
	global_store_dwordx2 v[120:121], v[202:203], off
	v_lshlrev_b32_e32 v202, 16, v200
	v_and_b32_e32 v203, 0xffff0000, v200
	v_lshlrev_b32_e32 v212, 16, v201
	v_and_b32_e32 v213, 0xffff0000, v201
	ds_read_b128 v[98:101], v222
	ds_read_b128 v[198:201], v222 offset:1152
	v_lshlrev_b32_e32 v214, 16, v196
	v_and_b32_e32 v215, 0xffff0000, v196
	v_lshlrev_b32_e32 v196, 16, v197
	v_and_b32_e32 v197, 0xffff0000, v197
	s_waitcnt lgkmcnt(1)
	v_pk_add_f32 v[102:103], v[100:101], v[212:213]
	v_pk_add_f32 v[104:105], v[98:99], v[202:203]
	s_waitcnt lgkmcnt(0)
	v_pk_add_f32 v[98:99], v[200:201], v[196:197]
	v_cvt_pk_bf16_f32 v196, v104, v105
	v_cvt_pk_bf16_f32 v197, v102, v103
	v_mul_f32_e32 v90, s33, v90
	v_pk_add_f32 v[100:101], v[198:199], v[214:215]
	v_cvt_pk_bf16_f32 v199, v98, v99
	v_mul_f32_e32 v82, s33, v82
	v_cvt_pk_bf16_f32 v198, v100, v101
	global_store_dwordx2 v[204:205], v[196:197], off offset:256
	global_store_dwordx2 v[120:121], v[198:199], off offset:256
	ds_write_b32 v140, v90
	v_mul_f32_e32 v90, s33, v94
	ds_write_b32 v140, v90 offset:64
	v_mul_f32_e32 v90, s33, v91
	ds_write_b32 v140, v90 offset:144
	v_mul_f32_e32 v90, s33, v95
	ds_write_b32 v140, v90 offset:208
	v_mul_f32_e32 v90, s33, v92
	ds_write_b32 v140, v90 offset:288
	v_mul_f32_e32 v90, s33, v96
	ds_write_b32 v140, v90 offset:352
	v_mul_f32_e32 v90, s33, v93
	ds_write_b32 v126, v90
	v_mul_f32_e32 v90, s33, v97
	ds_write_b32 v126, v90 offset:64
	v_lshlrev_b32_e32 v120, 16, v194
	v_and_b32_e32 v121, 0xffff0000, v194
	v_lshlrev_b32_e32 v198, 16, v195
	v_and_b32_e32 v199, 0xffff0000, v195
	ds_read_b128 v[90:93], v222
	ds_read_b128 v[194:197], v222 offset:1152
	ds_write_b32 v140, v82
	v_mul_f32_e32 v82, s33, v86
	ds_write_b32 v140, v82 offset:64
	v_mul_f32_e32 v82, s33, v83
	ds_write_b32 v140, v82 offset:144
	v_mul_f32_e32 v82, s33, v87
	ds_write_b32 v140, v82 offset:208
	v_mul_f32_e32 v82, s33, v84
	v_lshlrev_b32_e32 v200, 16, v192
	v_and_b32_e32 v201, 0xffff0000, v192
	v_lshl_add_u64 v[188:189], s[8:9], 0, v[188:189]
	ds_write_b32 v140, v82 offset:288
	v_mul_f32_e32 v82, s33, v88
	s_waitcnt lgkmcnt(6)
	v_pk_add_f32 v[94:95], v[92:93], v[198:199]
	v_pk_add_f32 v[96:97], v[90:91], v[120:121]
	s_waitcnt lgkmcnt(5)
	v_pk_add_f32 v[92:93], v[194:195], v[200:201]
	v_cvt_pk_bf16_f32 v120, v96, v97
	v_lshl_add_u64 v[194:195], v[188:189], 0, v[128:129]
	ds_write_b32 v140, v82 offset:352
	v_mul_f32_e32 v82, s33, v85
	v_lshlrev_b32_e32 v192, 16, v193
	v_and_b32_e32 v193, 0xffff0000, v193
	v_cvt_pk_bf16_f32 v121, v94, v95
	global_store_dwordx2 v[194:195], v[120:121], off
	v_add_co_u32_e32 v120, vcc, s81, v194
	ds_write_b32 v126, v82
	v_mul_f32_e32 v82, s33, v89
	v_pk_add_f32 v[90:91], v[196:197], v[192:193]
	v_cvt_pk_bf16_f32 v192, v92, v93
	v_addc_co_u32_e32 v121, vcc, 0, v195, vcc
	v_cvt_pk_bf16_f32 v193, v90, v91
	ds_write_b32 v126, v82 offset:64
	global_store_dwordx2 v[120:121], v[192:193], off
	v_lshlrev_b32_e32 v192, 16, v190
	v_and_b32_e32 v193, 0xffff0000, v190
	v_lshlrev_b32_e32 v196, 16, v191
	v_and_b32_e32 v197, 0xffff0000, v191
	ds_read_b128 v[82:85], v222
	ds_read_b128 v[188:191], v222 offset:1152
	v_lshlrev_b32_e32 v198, 16, v186
	v_and_b32_e32 v199, 0xffff0000, v186
	v_lshlrev_b32_e32 v186, 16, v187
	v_and_b32_e32 v187, 0xffff0000, v187
	s_waitcnt lgkmcnt(1)
	v_pk_add_f32 v[86:87], v[84:85], v[196:197]
	v_pk_add_f32 v[88:89], v[82:83], v[192:193]
	s_waitcnt lgkmcnt(0)
	v_pk_add_f32 v[82:83], v[190:191], v[186:187]
	v_cvt_pk_bf16_f32 v186, v88, v89
	v_cvt_pk_bf16_f32 v187, v86, v87
	v_mul_f32_e32 v74, s33, v74
	v_pk_add_f32 v[84:85], v[188:189], v[198:199]
	v_cvt_pk_bf16_f32 v189, v82, v83
	v_mul_f32_e32 v66, s33, v66
	v_cvt_pk_bf16_f32 v188, v84, v85
	global_store_dwordx2 v[194:195], v[186:187], off offset:256
	global_store_dwordx2 v[120:121], v[188:189], off offset:256
	ds_write_b32 v140, v74
	v_mul_f32_e32 v74, s33, v78
	ds_write_b32 v140, v74 offset:64
	v_mul_f32_e32 v74, s33, v75
	ds_write_b32 v140, v74 offset:144
	v_mul_f32_e32 v74, s33, v79
	ds_write_b32 v140, v74 offset:208
	v_mul_f32_e32 v74, s33, v76
	ds_write_b32 v140, v74 offset:288
	v_mul_f32_e32 v74, s33, v80
	ds_write_b32 v140, v74 offset:352
	v_mul_f32_e32 v74, s33, v77
	ds_write_b32 v126, v74
	v_mul_f32_e32 v74, s33, v81
	ds_write_b32 v126, v74 offset:64
	v_lshlrev_b32_e32 v120, 16, v184
	v_and_b32_e32 v121, 0xffff0000, v184
	v_lshlrev_b32_e32 v188, 16, v185
	v_and_b32_e32 v189, 0xffff0000, v185
	ds_read_b128 v[74:77], v222
	ds_read_b128 v[184:187], v222 offset:1152
	ds_write_b32 v140, v66
	v_mul_f32_e32 v66, s33, v70
	ds_write_b32 v140, v66 offset:64
	v_mul_f32_e32 v66, s33, v67
	ds_write_b32 v140, v66 offset:144
	v_mul_f32_e32 v66, s33, v71
	ds_write_b32 v140, v66 offset:208
	v_mul_f32_e32 v66, s33, v68
	v_lshlrev_b32_e32 v190, 16, v182
	v_and_b32_e32 v191, 0xffff0000, v182
	v_lshl_add_u64 v[178:179], s[8:9], 0, v[178:179]
	ds_write_b32 v140, v66 offset:288
	v_mul_f32_e32 v66, s33, v72
	s_waitcnt lgkmcnt(6)
	v_pk_add_f32 v[78:79], v[76:77], v[188:189]
	v_pk_add_f32 v[80:81], v[74:75], v[120:121]
	s_waitcnt lgkmcnt(5)
	v_pk_add_f32 v[76:77], v[184:185], v[190:191]
	v_cvt_pk_bf16_f32 v120, v80, v81
	v_lshl_add_u64 v[184:185], v[178:179], 0, v[128:129]
	ds_write_b32 v140, v66 offset:352
	v_mul_f32_e32 v66, s33, v69
	v_lshlrev_b32_e32 v182, 16, v183
	v_and_b32_e32 v183, 0xffff0000, v183
	v_cvt_pk_bf16_f32 v121, v78, v79
	global_store_dwordx2 v[184:185], v[120:121], off
	v_add_co_u32_e32 v120, vcc, s81, v184
	ds_write_b32 v126, v66
	v_mul_f32_e32 v66, s33, v73
	v_pk_add_f32 v[74:75], v[186:187], v[182:183]
	v_cvt_pk_bf16_f32 v182, v76, v77
	v_addc_co_u32_e32 v121, vcc, 0, v185, vcc
	v_cvt_pk_bf16_f32 v183, v74, v75
	ds_write_b32 v126, v66 offset:64
	global_store_dwordx2 v[120:121], v[182:183], off
	v_lshlrev_b32_e32 v182, 16, v180
	v_and_b32_e32 v183, 0xffff0000, v180
	v_lshlrev_b32_e32 v186, 16, v181
	v_and_b32_e32 v187, 0xffff0000, v181
	ds_read_b128 v[66:69], v222
	ds_read_b128 v[178:181], v222 offset:1152
	v_lshlrev_b32_e32 v188, 16, v176
	v_and_b32_e32 v189, 0xffff0000, v176
	v_lshlrev_b32_e32 v176, 16, v177
	v_and_b32_e32 v177, 0xffff0000, v177
	s_waitcnt lgkmcnt(1)
	v_pk_add_f32 v[70:71], v[68:69], v[186:187]
	v_pk_add_f32 v[72:73], v[66:67], v[182:183]
	s_waitcnt lgkmcnt(0)
	v_pk_add_f32 v[66:67], v[180:181], v[176:177]
	v_cvt_pk_bf16_f32 v176, v72, v73
	v_cvt_pk_bf16_f32 v177, v70, v71
	v_mul_f32_e32 v58, s33, v58
	v_pk_add_f32 v[68:69], v[178:179], v[188:189]
	v_cvt_pk_bf16_f32 v179, v66, v67
	v_mul_f32_e32 v50, s33, v50
	v_cvt_pk_bf16_f32 v178, v68, v69
	global_store_dwordx2 v[184:185], v[176:177], off offset:256
	global_store_dwordx2 v[120:121], v[178:179], off offset:256
	ds_write_b32 v140, v58
	v_mul_f32_e32 v58, s33, v62
	ds_write_b32 v140, v58 offset:64
	v_mul_f32_e32 v58, s33, v59
	ds_write_b32 v140, v58 offset:144
	v_mul_f32_e32 v58, s33, v63
	ds_write_b32 v140, v58 offset:208
	v_mul_f32_e32 v58, s33, v60
	ds_write_b32 v140, v58 offset:288
	v_mul_f32_e32 v58, s33, v64
	ds_write_b32 v140, v58 offset:352
	v_mul_f32_e32 v58, s33, v61
	ds_write_b32 v126, v58
	v_mul_f32_e32 v58, s33, v65
	ds_write_b32 v126, v58 offset:64
	v_lshlrev_b32_e32 v120, 16, v174
	v_and_b32_e32 v121, 0xffff0000, v174
	v_lshlrev_b32_e32 v178, 16, v175
	v_and_b32_e32 v179, 0xffff0000, v175
	ds_read_b128 v[58:61], v222
	ds_read_b128 v[174:177], v222 offset:1152
	ds_write_b32 v140, v50
	v_mul_f32_e32 v50, s33, v54
	ds_write_b32 v140, v50 offset:64
	v_mul_f32_e32 v50, s33, v51
	ds_write_b32 v140, v50 offset:144
	v_mul_f32_e32 v50, s33, v55
	ds_write_b32 v140, v50 offset:208
	v_mul_f32_e32 v50, s33, v52
	v_lshlrev_b32_e32 v180, 16, v172
	v_and_b32_e32 v181, 0xffff0000, v172
	v_lshl_add_u64 v[168:169], s[8:9], 0, v[168:169]
	ds_write_b32 v140, v50 offset:288
	v_mul_f32_e32 v50, s33, v56
	s_waitcnt lgkmcnt(6)
	v_pk_add_f32 v[62:63], v[60:61], v[178:179]
	v_pk_add_f32 v[64:65], v[58:59], v[120:121]
	s_waitcnt lgkmcnt(5)
	v_pk_add_f32 v[60:61], v[174:175], v[180:181]
	v_cvt_pk_bf16_f32 v120, v64, v65
	v_lshl_add_u64 v[174:175], v[168:169], 0, v[128:129]
	ds_write_b32 v140, v50 offset:352
	v_mul_f32_e32 v50, s33, v53
	v_lshlrev_b32_e32 v172, 16, v173
	v_and_b32_e32 v173, 0xffff0000, v173
	v_cvt_pk_bf16_f32 v121, v62, v63
	global_store_dwordx2 v[174:175], v[120:121], off
	v_add_co_u32_e32 v120, vcc, s81, v174
	ds_write_b32 v126, v50
	v_mul_f32_e32 v50, s33, v57
	v_pk_add_f32 v[58:59], v[176:177], v[172:173]
	v_cvt_pk_bf16_f32 v172, v60, v61
	v_addc_co_u32_e32 v121, vcc, 0, v175, vcc
	v_cvt_pk_bf16_f32 v173, v58, v59
	ds_write_b32 v126, v50 offset:64
	global_store_dwordx2 v[120:121], v[172:173], off
	v_lshlrev_b32_e32 v172, 16, v170
	v_and_b32_e32 v173, 0xffff0000, v170
	v_lshlrev_b32_e32 v176, 16, v171
	v_and_b32_e32 v177, 0xffff0000, v171
	ds_read_b128 v[50:53], v222
	ds_read_b128 v[168:171], v222 offset:1152
	v_lshlrev_b32_e32 v178, 16, v166
	v_and_b32_e32 v179, 0xffff0000, v166
	v_lshlrev_b32_e32 v166, 16, v167
	v_and_b32_e32 v167, 0xffff0000, v167
	s_waitcnt lgkmcnt(1)
	v_pk_add_f32 v[54:55], v[52:53], v[176:177]
	v_pk_add_f32 v[56:57], v[50:51], v[172:173]
	s_waitcnt lgkmcnt(0)
	v_pk_add_f32 v[50:51], v[170:171], v[166:167]
	v_cvt_pk_bf16_f32 v166, v56, v57
	v_cvt_pk_bf16_f32 v167, v54, v55
	v_mul_f32_e32 v42, s33, v42
	v_pk_add_f32 v[52:53], v[168:169], v[178:179]
	v_cvt_pk_bf16_f32 v169, v50, v51
	v_mul_f32_e32 v34, s33, v34
	v_cvt_pk_bf16_f32 v168, v52, v53
	global_store_dwordx2 v[174:175], v[166:167], off offset:256
	global_store_dwordx2 v[120:121], v[168:169], off offset:256
	ds_write_b32 v140, v42
	v_mul_f32_e32 v42, s33, v46
	ds_write_b32 v140, v42 offset:64
	v_mul_f32_e32 v42, s33, v43
	ds_write_b32 v140, v42 offset:144
	v_mul_f32_e32 v42, s33, v47
	ds_write_b32 v140, v42 offset:208
	v_mul_f32_e32 v42, s33, v44
	ds_write_b32 v140, v42 offset:288
	v_mul_f32_e32 v42, s33, v48
	ds_write_b32 v140, v42 offset:352
	v_mul_f32_e32 v42, s33, v45
	ds_write_b32 v126, v42
	v_mul_f32_e32 v42, s33, v49
	ds_write_b32 v126, v42 offset:64
	v_lshlrev_b32_e32 v120, 16, v164
	v_and_b32_e32 v121, 0xffff0000, v164
	v_lshlrev_b32_e32 v168, 16, v165
	v_and_b32_e32 v169, 0xffff0000, v165
	ds_read_b128 v[42:45], v222
	ds_read_b128 v[164:167], v222 offset:1152
	ds_write_b32 v140, v34
	v_mul_f32_e32 v34, s33, v38
	ds_write_b32 v140, v34 offset:64
	v_mul_f32_e32 v34, s33, v35
	ds_write_b32 v140, v34 offset:144
	v_mul_f32_e32 v34, s33, v39
	ds_write_b32 v140, v34 offset:208
	v_mul_f32_e32 v34, s33, v36
	v_lshlrev_b32_e32 v170, 16, v162
	v_and_b32_e32 v171, 0xffff0000, v162
	v_lshl_add_u64 v[158:159], s[8:9], 0, v[158:159]
	ds_write_b32 v140, v34 offset:288
	v_mul_f32_e32 v34, s33, v40
	s_waitcnt lgkmcnt(6)
	v_pk_add_f32 v[46:47], v[44:45], v[168:169]
	v_pk_add_f32 v[48:49], v[42:43], v[120:121]
	s_waitcnt lgkmcnt(5)
	v_pk_add_f32 v[44:45], v[164:165], v[170:171]
	v_cvt_pk_bf16_f32 v120, v48, v49
	v_lshl_add_u64 v[164:165], v[158:159], 0, v[128:129]
	ds_write_b32 v140, v34 offset:352
	v_mul_f32_e32 v34, s33, v37
	v_lshlrev_b32_e32 v162, 16, v163
	v_and_b32_e32 v163, 0xffff0000, v163
	v_cvt_pk_bf16_f32 v121, v46, v47
	global_store_dwordx2 v[164:165], v[120:121], off
	v_add_co_u32_e32 v120, vcc, s81, v164
	ds_write_b32 v126, v34
	v_mul_f32_e32 v34, s33, v41
	v_pk_add_f32 v[42:43], v[166:167], v[162:163]
	v_cvt_pk_bf16_f32 v162, v44, v45
	v_addc_co_u32_e32 v121, vcc, 0, v165, vcc
	v_cvt_pk_bf16_f32 v163, v42, v43
	ds_write_b32 v126, v34 offset:64
	global_store_dwordx2 v[120:121], v[162:163], off
	v_lshlrev_b32_e32 v162, 16, v160
	v_and_b32_e32 v163, 0xffff0000, v160
	v_lshlrev_b32_e32 v166, 16, v161
	v_and_b32_e32 v167, 0xffff0000, v161
	ds_read_b128 v[34:37], v222
	ds_read_b128 v[158:161], v222 offset:1152
	v_lshlrev_b32_e32 v168, 16, v156
	v_and_b32_e32 v169, 0xffff0000, v156
	v_lshlrev_b32_e32 v156, 16, v157
	v_and_b32_e32 v157, 0xffff0000, v157
	s_waitcnt lgkmcnt(1)
	v_pk_add_f32 v[38:39], v[36:37], v[166:167]
	v_pk_add_f32 v[40:41], v[34:35], v[162:163]
	s_waitcnt lgkmcnt(0)
	v_pk_add_f32 v[34:35], v[160:161], v[156:157]
	v_cvt_pk_bf16_f32 v156, v40, v41
	v_cvt_pk_bf16_f32 v157, v38, v39
	v_mul_f32_e32 v26, s33, v26
	v_pk_add_f32 v[36:37], v[158:159], v[168:169]
	v_cvt_pk_bf16_f32 v159, v34, v35
	v_mul_f32_e32 v18, s33, v18
	v_cvt_pk_bf16_f32 v158, v36, v37
	global_store_dwordx2 v[164:165], v[156:157], off offset:256
	global_store_dwordx2 v[120:121], v[158:159], off offset:256
	ds_write_b32 v140, v26
	v_mul_f32_e32 v26, s33, v30
	ds_write_b32 v140, v26 offset:64
	v_mul_f32_e32 v26, s33, v27
	ds_write_b32 v140, v26 offset:144
	v_mul_f32_e32 v26, s33, v31
	ds_write_b32 v140, v26 offset:208
	v_mul_f32_e32 v26, s33, v28
	ds_write_b32 v140, v26 offset:288
	v_mul_f32_e32 v26, s33, v32
	ds_write_b32 v140, v26 offset:352
	v_mul_f32_e32 v26, s33, v29
	ds_write_b32 v126, v26
	v_mul_f32_e32 v26, s33, v33
	ds_write_b32 v126, v26 offset:64
	v_lshlrev_b32_e32 v120, 16, v154
	v_and_b32_e32 v121, 0xffff0000, v154
	v_lshlrev_b32_e32 v158, 16, v155
	v_and_b32_e32 v159, 0xffff0000, v155
	ds_read_b128 v[26:29], v222
	ds_read_b128 v[154:157], v222 offset:1152
	ds_write_b32 v140, v18
	v_mul_f32_e32 v18, s33, v22
	ds_write_b32 v140, v18 offset:64
	v_mul_f32_e32 v18, s33, v19
	ds_write_b32 v140, v18 offset:144
	v_mul_f32_e32 v18, s33, v23
	ds_write_b32 v140, v18 offset:208
	v_mul_f32_e32 v18, s33, v20
	v_lshlrev_b32_e32 v160, 16, v152
	v_and_b32_e32 v161, 0xffff0000, v152
	v_lshl_add_u64 v[148:149], s[8:9], 0, v[148:149]
	ds_write_b32 v140, v18 offset:288
	v_mul_f32_e32 v18, s33, v24
	s_waitcnt lgkmcnt(6)
	v_pk_add_f32 v[30:31], v[28:29], v[158:159]
	v_pk_add_f32 v[32:33], v[26:27], v[120:121]
	s_waitcnt lgkmcnt(5)
	v_pk_add_f32 v[28:29], v[154:155], v[160:161]
	v_cvt_pk_bf16_f32 v120, v32, v33
	v_lshl_add_u64 v[154:155], v[148:149], 0, v[128:129]
	ds_write_b32 v140, v18 offset:352
	v_mul_f32_e32 v18, s33, v21
	v_lshlrev_b32_e32 v152, 16, v153
	v_and_b32_e32 v153, 0xffff0000, v153
	v_cvt_pk_bf16_f32 v121, v30, v31
	global_store_dwordx2 v[154:155], v[120:121], off
	v_add_co_u32_e32 v120, vcc, s81, v154
	ds_write_b32 v126, v18
	v_mul_f32_e32 v18, s33, v25
	v_pk_add_f32 v[26:27], v[156:157], v[152:153]
	v_cvt_pk_bf16_f32 v152, v28, v29
	v_addc_co_u32_e32 v121, vcc, 0, v155, vcc
	v_cvt_pk_bf16_f32 v153, v26, v27
	ds_write_b32 v126, v18 offset:64
	global_store_dwordx2 v[120:121], v[152:153], off
	v_lshlrev_b32_e32 v152, 16, v150
	v_and_b32_e32 v153, 0xffff0000, v150
	v_lshlrev_b32_e32 v156, 16, v151
	v_and_b32_e32 v157, 0xffff0000, v151
	ds_read_b128 v[18:21], v222
	ds_read_b128 v[148:151], v222 offset:1152
	v_lshlrev_b32_e32 v158, 16, v146
	v_and_b32_e32 v159, 0xffff0000, v146
	v_lshlrev_b32_e32 v146, 16, v147
	v_and_b32_e32 v147, 0xffff0000, v147
	s_waitcnt lgkmcnt(1)
	v_pk_add_f32 v[22:23], v[20:21], v[156:157]
	v_pk_add_f32 v[24:25], v[18:19], v[152:153]
	s_waitcnt lgkmcnt(0)
	v_pk_add_f32 v[18:19], v[150:151], v[146:147]
	v_cvt_pk_bf16_f32 v146, v24, v25
	v_cvt_pk_bf16_f32 v147, v22, v23
	v_mul_f32_e32 v10, s33, v10
	v_pk_add_f32 v[20:21], v[148:149], v[158:159]
	v_cvt_pk_bf16_f32 v149, v18, v19
	v_mul_f32_e32 v2, s33, v2
	v_cvt_pk_bf16_f32 v148, v20, v21
	global_store_dwordx2 v[154:155], v[146:147], off offset:256
	global_store_dwordx2 v[120:121], v[148:149], off offset:256
	ds_write_b32 v140, v10
	v_mul_f32_e32 v10, s33, v14
	ds_write_b32 v140, v10 offset:64
	v_mul_f32_e32 v10, s33, v11
	ds_write_b32 v140, v10 offset:144
	v_mul_f32_e32 v10, s33, v15
	ds_write_b32 v140, v10 offset:208
	v_mul_f32_e32 v10, s33, v12
	ds_write_b32 v140, v10 offset:288
	v_mul_f32_e32 v10, s33, v16
	ds_write_b32 v140, v10 offset:352
	v_mul_f32_e32 v10, s33, v13
	ds_write_b32 v126, v10
	v_mul_f32_e32 v10, s33, v17
	ds_write_b32 v126, v10 offset:64
	v_lshlrev_b32_e32 v120, 16, v144
	v_and_b32_e32 v121, 0xffff0000, v144
	v_lshlrev_b32_e32 v148, 16, v145
	v_and_b32_e32 v149, 0xffff0000, v145
	ds_read_b128 v[10:13], v222
	ds_read_b128 v[144:147], v222 offset:1152
	ds_write_b32 v140, v2
	v_mul_f32_e32 v2, s33, v6
	ds_write_b32 v140, v2 offset:64
	v_mul_f32_e32 v2, s33, v3
	ds_write_b32 v140, v2 offset:144
	v_mul_f32_e32 v2, s33, v7
	ds_write_b32 v140, v2 offset:208
	v_mul_f32_e32 v2, s33, v4
	ds_write_b32 v140, v2 offset:288
	v_mul_f32_e32 v2, s33, v8
	ds_write_b32 v140, v2 offset:352
	v_mul_f32_e32 v2, s33, v5
	ds_write_b32 v126, v2
	v_mul_f32_e32 v2, s33, v9
	ds_write_b32 v126, v2 offset:64
	ds_read_b128 v[2:5], v222
	v_lshl_add_u64 v[136:137], s[8:9], 0, v[136:137]
	v_fmac_f32_e32 v118, v226, v226
	s_waitcnt lgkmcnt(10)
	v_pk_add_f32 v[14:15], v[12:13], v[148:149]
	v_pk_add_f32 v[16:17], v[10:11], v[120:121]
	v_cvt_pk_bf16_f32 v121, v14, v15
	v_lshl_add_u64 v[136:137], v[136:137], 0, v[128:129]
	v_cvt_pk_bf16_f32 v120, v16, v17
	v_fmac_f32_e32 v118, v227, v227
	v_lshlrev_b32_e32 v150, 16, v142
	v_and_b32_e32 v151, 0xffff0000, v142
	global_store_dwordx2 v[136:137], v[120:121], off
	v_lshlrev_b32_e32 v120, 16, v138
	v_and_b32_e32 v121, 0xffff0000, v138
	v_add_f32_e32 v118, v127, v118
	s_waitcnt lgkmcnt(9)
	v_pk_add_f32 v[12:13], v[144:145], v[150:151]
	v_add_co_u32_e32 v144, vcc, s81, v136
	ds_read_b128 v[126:129], v222 offset:1152
	s_waitcnt lgkmcnt(1)
	v_pk_add_f32 v[8:9], v[2:3], v[120:121]
	v_and_b32_e32 v120, 64, v209
	v_addc_co_u32_e32 v145, vcc, 0, v137, vcc
	v_xor_b32_e32 v119, 1, v209
	v_add_u32_e32 v121, 64, v120
	v_lshlrev_b32_e32 v142, 16, v143
	v_and_b32_e32 v143, 0xffff0000, v143
	v_cmp_lt_i32_e32 vcc, v119, v121
	v_pk_add_f32 v[10:11], v[146:147], v[142:143]
	v_cvt_pk_bf16_f32 v142, v12, v13
	v_lshlrev_b32_e32 v138, 16, v139
	v_cvt_pk_bf16_f32 v143, v10, v11
	v_cndmask_b32_e32 v119, v209, v119, vcc
	global_store_dwordx2 v[144:145], v[142:143], off
	v_and_b32_e32 v139, 0xffff0000, v139
	v_lshlrev_b32_e32 v142, 16, v134
	v_and_b32_e32 v143, 0xffff0000, v134
	v_lshlrev_b32_e32 v119, 2, v119
	v_pk_add_f32 v[6:7], v[4:5], v[138:139]
	s_waitcnt lgkmcnt(0)
	v_pk_add_f32 v[4:5], v[126:127], v[142:143]
	s_nop 1
	v_mov_b32_dpp v126, v118 quad_perm:[1,0,3,2] row_mask:0xf bank_mask:0xf
	v_xor_b32_e32 v120, 2, v209
	v_cmp_lt_i32_e32 vcc, v120, v121
	v_xor_b32_e32 v127, 4, v209
	v_lshlrev_b32_e32 v134, 16, v135
	v_cndmask_b32_e32 v120, v209, v120, vcc
	v_lshlrev_b32_e32 v120, 2, v120
	s_waitcnt lgkmcnt(0)
	v_add_f32_e32 v118, v118, v126
	s_nop 1
	v_mov_b32_dpp v126, v118 quad_perm:[2,3,0,1] row_mask:0xf bank_mask:0xf
	v_cmp_lt_i32_e32 vcc, v127, v121
	v_and_b32_e32 v135, 0xffff0000, v135
	v_pk_add_f32 v[2:3], v[128:129], v[134:135]
	v_cndmask_b32_e32 v121, v209, v127, vcc
	v_lshlrev_b32_e32 v121, 2, v121
	s_waitcnt lgkmcnt(0)
	v_add_f32_e32 v126, v118, v126
	s_nop 1
	v_mov_b32_dpp v127, v126 row_half_mirror row_mask:0xf bank_mask:0xf
	v_cvt_pk_bf16_f32 v128, v8, v9
	v_cvt_pk_bf16_f32 v129, v6, v7
	v_cmp_eq_u32_e32 vcc, 0, v221
	v_lshl_add_u32 v118, v220, 2, s39
	v_cvt_pk_bf16_f32 v134, v4, v5
	v_cvt_pk_bf16_f32 v135, v2, v3
	global_store_dwordx2 v[136:137], v[128:129], off offset:256
	global_store_dwordx2 v[144:145], v[134:135], off offset:256
	s_and_saveexec_b64 s[20:21], vcc
	s_cbranch_execz .LBB0_408
	s_waitcnt lgkmcnt(0)
	v_add_f32_e32 v126, v126, v127
	ds_write_b32 v118, v126
.LBB0_408:
	s_or_b64 exec, exec, s[20:21]
	v_mul_f32_e32 v125, v125, v125
	v_mul_f32_e32 v117, v117, v117
	v_fmac_f32_e32 v125, v124, v124
	v_fmac_f32_e32 v117, v116, v116
	v_fmac_f32_e32 v125, v122, v122
	v_fmac_f32_e32 v117, v114, v114
	v_fmac_f32_e32 v125, v123, v123
	v_fmac_f32_e32 v117, v115, v115
	v_add_f32_e32 v114, v125, v117
	s_nop 1
	v_mov_b32_dpp v115, v114 quad_perm:[1,0,3,2] row_mask:0xf bank_mask:0xf
	s_waitcnt lgkmcnt(0)
	v_add_f32_e32 v114, v114, v115
	s_nop 1
	v_mov_b32_dpp v115, v114 quad_perm:[2,3,0,1] row_mask:0xf bank_mask:0xf
	s_waitcnt lgkmcnt(0)
	v_add_f32_e32 v114, v114, v115
	s_nop 1
	v_mov_b32_dpp v115, v114 row_half_mirror row_mask:0xf bank_mask:0xf
	s_and_saveexec_b64 s[20:21], vcc
	s_cbranch_execz .LBB0_410
	s_waitcnt lgkmcnt(0)
	v_add_f32_e32 v114, v114, v115
	ds_write_b32 v118, v114 offset:32
.LBB0_410:
	s_or_b64 exec, exec, s[20:21]
	v_mul_f32_e32 v113, v113, v113
	v_mul_f32_e32 v105, v105, v105
	v_fmac_f32_e32 v113, v112, v112
	v_fmac_f32_e32 v105, v104, v104
	v_fmac_f32_e32 v113, v110, v110
	v_fmac_f32_e32 v105, v102, v102
	v_fmac_f32_e32 v113, v111, v111
	v_fmac_f32_e32 v105, v103, v103
	v_add_f32_e32 v102, v113, v105
	s_nop 1
	v_mov_b32_dpp v103, v102 quad_perm:[1,0,3,2] row_mask:0xf bank_mask:0xf
	s_waitcnt lgkmcnt(0)
	v_add_f32_e32 v102, v102, v103
	s_nop 1
	v_mov_b32_dpp v103, v102 quad_perm:[2,3,0,1] row_mask:0xf bank_mask:0xf
	s_waitcnt lgkmcnt(0)
	v_add_f32_e32 v102, v102, v103
	s_nop 1
	v_mov_b32_dpp v103, v102 row_half_mirror row_mask:0xf bank_mask:0xf
	s_and_saveexec_b64 s[20:21], vcc
	s_cbranch_execz .LBB0_412
	s_waitcnt lgkmcnt(0)
	v_add_f32_e32 v102, v102, v103
	ds_write_b32 v118, v102 offset:64
.LBB0_412:
	s_or_b64 exec, exec, s[20:21]
	v_mul_f32_e32 v102, v109, v109
	v_mul_f32_e32 v101, v101, v101
	v_fmac_f32_e32 v102, v108, v108
	v_fmac_f32_e32 v101, v100, v100
	v_fmac_f32_e32 v102, v106, v106
	v_fmac_f32_e32 v101, v98, v98
	v_fmac_f32_e32 v102, v107, v107
	v_fmac_f32_e32 v101, v99, v99
	v_add_f32_e32 v98, v102, v101
	s_nop 1
	v_mov_b32_dpp v99, v98 quad_perm:[1,0,3,2] row_mask:0xf bank_mask:0xf
	s_waitcnt lgkmcnt(0)
	v_add_f32_e32 v98, v98, v99
	s_nop 1
	v_mov_b32_dpp v99, v98 quad_perm:[2,3,0,1] row_mask:0xf bank_mask:0xf
	s_waitcnt lgkmcnt(0)
	v_add_f32_e32 v98, v98, v99
	s_nop 1
	v_mov_b32_dpp v99, v98 row_half_mirror row_mask:0xf bank_mask:0xf
	s_and_saveexec_b64 s[20:21], vcc
	s_cbranch_execz .LBB0_414
	s_waitcnt lgkmcnt(0)
	v_add_f32_e32 v98, v98, v99
	ds_write_b32 v118, v98 offset:96
.LBB0_414:
	s_or_b64 exec, exec, s[20:21]
	v_mul_f32_e32 v97, v97, v97
	v_mul_f32_e32 v89, v89, v89
	v_fmac_f32_e32 v97, v96, v96
	v_fmac_f32_e32 v89, v88, v88
	v_fmac_f32_e32 v97, v94, v94
	v_fmac_f32_e32 v89, v86, v86
	v_fmac_f32_e32 v97, v95, v95
	v_fmac_f32_e32 v89, v87, v87
	v_add_f32_e32 v86, v97, v89
	s_nop 1
	v_mov_b32_dpp v87, v86 quad_perm:[1,0,3,2] row_mask:0xf bank_mask:0xf
	s_waitcnt lgkmcnt(0)
	v_add_f32_e32 v86, v86, v87
	s_nop 1
	v_mov_b32_dpp v87, v86 quad_perm:[2,3,0,1] row_mask:0xf bank_mask:0xf
	s_waitcnt lgkmcnt(0)
	v_add_f32_e32 v86, v86, v87
	s_nop 1
	v_mov_b32_dpp v87, v86 row_half_mirror row_mask:0xf bank_mask:0xf
	s_and_saveexec_b64 s[20:21], vcc
	s_cbranch_execz .LBB0_416
	s_waitcnt lgkmcnt(0)
	v_add_f32_e32 v86, v86, v87
	ds_write_b32 v118, v86 offset:128
.LBB0_416:
	s_or_b64 exec, exec, s[20:21]
	v_mul_f32_e32 v86, v93, v93
	v_mul_f32_e32 v85, v85, v85
	v_fmac_f32_e32 v86, v92, v92
	v_fmac_f32_e32 v85, v84, v84
	v_fmac_f32_e32 v86, v90, v90
	v_fmac_f32_e32 v85, v82, v82
	v_fmac_f32_e32 v86, v91, v91
	v_fmac_f32_e32 v85, v83, v83
	v_add_f32_e32 v82, v86, v85
	s_nop 1
	v_mov_b32_dpp v83, v82 quad_perm:[1,0,3,2] row_mask:0xf bank_mask:0xf
	s_waitcnt lgkmcnt(0)
	v_add_f32_e32 v82, v82, v83
	s_nop 1
	v_mov_b32_dpp v83, v82 quad_perm:[2,3,0,1] row_mask:0xf bank_mask:0xf
	s_waitcnt lgkmcnt(0)
	v_add_f32_e32 v82, v82, v83
	s_nop 1
	v_mov_b32_dpp v83, v82 row_half_mirror row_mask:0xf bank_mask:0xf
	s_and_saveexec_b64 s[20:21], vcc
	s_cbranch_execz .LBB0_418
	s_waitcnt lgkmcnt(0)
	v_add_f32_e32 v82, v82, v83
	ds_write_b32 v118, v82 offset:160
.LBB0_418:
	s_or_b64 exec, exec, s[20:21]
	v_mul_f32_e32 v81, v81, v81
	v_mul_f32_e32 v73, v73, v73
	v_fmac_f32_e32 v81, v80, v80
	v_fmac_f32_e32 v73, v72, v72
	v_fmac_f32_e32 v81, v78, v78
	v_fmac_f32_e32 v73, v70, v70
	v_fmac_f32_e32 v81, v79, v79
	v_fmac_f32_e32 v73, v71, v71
	v_add_f32_e32 v70, v81, v73
	s_nop 1
	v_mov_b32_dpp v71, v70 quad_perm:[1,0,3,2] row_mask:0xf bank_mask:0xf
	s_waitcnt lgkmcnt(0)
	v_add_f32_e32 v70, v70, v71
	s_nop 1
	v_mov_b32_dpp v71, v70 quad_perm:[2,3,0,1] row_mask:0xf bank_mask:0xf
	s_waitcnt lgkmcnt(0)
	v_add_f32_e32 v70, v70, v71
	s_nop 1
	v_mov_b32_dpp v71, v70 row_half_mirror row_mask:0xf bank_mask:0xf
	s_and_saveexec_b64 s[20:21], vcc
	s_cbranch_execz .LBB0_420
	s_waitcnt lgkmcnt(0)
	v_add_f32_e32 v70, v70, v71
	ds_write_b32 v118, v70 offset:192
.LBB0_420:
	s_or_b64 exec, exec, s[20:21]
	v_mul_f32_e32 v70, v77, v77
	v_mul_f32_e32 v69, v69, v69
	v_fmac_f32_e32 v70, v76, v76
	v_fmac_f32_e32 v69, v68, v68
	v_fmac_f32_e32 v70, v74, v74
	v_fmac_f32_e32 v69, v66, v66
	v_fmac_f32_e32 v70, v75, v75
	v_fmac_f32_e32 v69, v67, v67
	v_add_f32_e32 v66, v70, v69
	s_nop 1
	v_mov_b32_dpp v67, v66 quad_perm:[1,0,3,2] row_mask:0xf bank_mask:0xf
	s_waitcnt lgkmcnt(0)
	v_add_f32_e32 v66, v66, v67
	s_nop 1
	v_mov_b32_dpp v67, v66 quad_perm:[2,3,0,1] row_mask:0xf bank_mask:0xf
	s_waitcnt lgkmcnt(0)
	v_add_f32_e32 v66, v66, v67
	s_nop 1
	v_mov_b32_dpp v67, v66 row_half_mirror row_mask:0xf bank_mask:0xf
	s_and_saveexec_b64 s[20:21], vcc
	s_cbranch_execz .LBB0_422
	s_waitcnt lgkmcnt(0)
	v_add_f32_e32 v66, v66, v67
	ds_write_b32 v118, v66 offset:224
.LBB0_422:
	s_or_b64 exec, exec, s[20:21]
	v_mul_f32_e32 v65, v65, v65
	v_mul_f32_e32 v57, v57, v57
	v_fmac_f32_e32 v65, v64, v64
	v_fmac_f32_e32 v57, v56, v56
	v_fmac_f32_e32 v65, v62, v62
	v_fmac_f32_e32 v57, v54, v54
	v_fmac_f32_e32 v65, v63, v63
	v_fmac_f32_e32 v57, v55, v55
	v_add_f32_e32 v54, v65, v57
	s_nop 1
	v_mov_b32_dpp v55, v54 quad_perm:[1,0,3,2] row_mask:0xf bank_mask:0xf
	s_waitcnt lgkmcnt(0)
	v_add_f32_e32 v54, v54, v55
	s_nop 1
	v_mov_b32_dpp v55, v54 quad_perm:[2,3,0,1] row_mask:0xf bank_mask:0xf
	s_waitcnt lgkmcnt(0)
	v_add_f32_e32 v54, v54, v55
	s_nop 1
	v_mov_b32_dpp v55, v54 row_half_mirror row_mask:0xf bank_mask:0xf
	s_and_saveexec_b64 s[20:21], vcc
	s_cbranch_execz .LBB0_424
	s_waitcnt lgkmcnt(0)
	v_add_f32_e32 v54, v54, v55
	ds_write_b32 v118, v54 offset:512
.LBB0_424:
	s_or_b64 exec, exec, s[20:21]
	v_mul_f32_e32 v54, v61, v61
	v_mul_f32_e32 v53, v53, v53
	v_fmac_f32_e32 v54, v60, v60
	v_fmac_f32_e32 v53, v52, v52
	v_fmac_f32_e32 v54, v58, v58
	v_fmac_f32_e32 v53, v50, v50
	v_fmac_f32_e32 v54, v59, v59
	v_fmac_f32_e32 v53, v51, v51
	v_add_f32_e32 v50, v54, v53
	s_nop 1
	v_mov_b32_dpp v51, v50 quad_perm:[1,0,3,2] row_mask:0xf bank_mask:0xf
	s_waitcnt lgkmcnt(0)
	v_add_f32_e32 v50, v50, v51
	s_nop 1
	v_mov_b32_dpp v51, v50 quad_perm:[2,3,0,1] row_mask:0xf bank_mask:0xf
	s_waitcnt lgkmcnt(0)
	v_add_f32_e32 v50, v50, v51
	s_nop 1
	v_mov_b32_dpp v51, v50 row_half_mirror row_mask:0xf bank_mask:0xf
	s_and_saveexec_b64 s[20:21], vcc
	s_cbranch_execz .LBB0_426
	s_waitcnt lgkmcnt(0)
	v_add_f32_e32 v50, v50, v51
	ds_write_b32 v118, v50 offset:544
.LBB0_426:
	s_or_b64 exec, exec, s[20:21]
	v_mul_f32_e32 v49, v49, v49
	v_mul_f32_e32 v41, v41, v41
	v_fmac_f32_e32 v49, v48, v48
	v_fmac_f32_e32 v41, v40, v40
	v_fmac_f32_e32 v49, v46, v46
	v_fmac_f32_e32 v41, v38, v38
	v_fmac_f32_e32 v49, v47, v47
	v_fmac_f32_e32 v41, v39, v39
	v_add_f32_e32 v38, v49, v41
	s_nop 1
	v_mov_b32_dpp v39, v38 quad_perm:[1,0,3,2] row_mask:0xf bank_mask:0xf
	s_waitcnt lgkmcnt(0)
	v_add_f32_e32 v38, v38, v39
	s_nop 1
	v_mov_b32_dpp v39, v38 quad_perm:[2,3,0,1] row_mask:0xf bank_mask:0xf
	s_waitcnt lgkmcnt(0)
	v_add_f32_e32 v38, v38, v39
	s_nop 1
	v_mov_b32_dpp v39, v38 row_half_mirror row_mask:0xf bank_mask:0xf
	s_and_saveexec_b64 s[20:21], vcc
	s_cbranch_execz .LBB0_428
	s_waitcnt lgkmcnt(0)
	v_add_f32_e32 v38, v38, v39
	ds_write_b32 v118, v38 offset:576
.LBB0_428:
	s_or_b64 exec, exec, s[20:21]
	v_mul_f32_e32 v38, v45, v45
	v_mul_f32_e32 v37, v37, v37
	v_fmac_f32_e32 v38, v44, v44
	v_fmac_f32_e32 v37, v36, v36
	v_fmac_f32_e32 v38, v42, v42
	v_fmac_f32_e32 v37, v34, v34
	v_fmac_f32_e32 v38, v43, v43
	v_fmac_f32_e32 v37, v35, v35
	v_add_f32_e32 v34, v38, v37
	s_nop 1
	v_mov_b32_dpp v35, v34 quad_perm:[1,0,3,2] row_mask:0xf bank_mask:0xf
	s_waitcnt lgkmcnt(0)
	v_add_f32_e32 v34, v34, v35
	s_nop 1
	v_mov_b32_dpp v35, v34 quad_perm:[2,3,0,1] row_mask:0xf bank_mask:0xf
	s_waitcnt lgkmcnt(0)
	v_add_f32_e32 v34, v34, v35
	s_nop 1
	v_mov_b32_dpp v35, v34 row_half_mirror row_mask:0xf bank_mask:0xf
	s_and_saveexec_b64 s[20:21], vcc
	s_cbranch_execz .LBB0_430
	s_waitcnt lgkmcnt(0)
	v_add_f32_e32 v34, v34, v35
	ds_write_b32 v118, v34 offset:608
.LBB0_430:
	s_or_b64 exec, exec, s[20:21]
	v_mul_f32_e32 v33, v33, v33
	v_mul_f32_e32 v25, v25, v25
	v_fmac_f32_e32 v33, v32, v32
	v_fmac_f32_e32 v25, v24, v24
	v_fmac_f32_e32 v33, v30, v30
	v_fmac_f32_e32 v25, v22, v22
	v_fmac_f32_e32 v33, v31, v31
	v_fmac_f32_e32 v25, v23, v23
	v_add_f32_e32 v22, v33, v25
	s_nop 1
	v_mov_b32_dpp v23, v22 quad_perm:[1,0,3,2] row_mask:0xf bank_mask:0xf
	s_waitcnt lgkmcnt(0)
	v_add_f32_e32 v22, v22, v23
	s_nop 1
	v_mov_b32_dpp v23, v22 quad_perm:[2,3,0,1] row_mask:0xf bank_mask:0xf
	s_waitcnt lgkmcnt(0)
	v_add_f32_e32 v22, v22, v23
	s_nop 1
	v_mov_b32_dpp v23, v22 row_half_mirror row_mask:0xf bank_mask:0xf
	s_and_saveexec_b64 s[20:21], vcc
	s_cbranch_execz .LBB0_432
	s_waitcnt lgkmcnt(0)
	v_add_f32_e32 v22, v22, v23
	ds_write_b32 v118, v22 offset:640
.LBB0_432:
	s_or_b64 exec, exec, s[20:21]
	v_mul_f32_e32 v22, v29, v29
	v_mul_f32_e32 v21, v21, v21
	v_fmac_f32_e32 v22, v28, v28
	v_fmac_f32_e32 v21, v20, v20
	v_fmac_f32_e32 v22, v26, v26
	v_fmac_f32_e32 v21, v18, v18
	v_fmac_f32_e32 v22, v27, v27
	v_fmac_f32_e32 v21, v19, v19
	v_add_f32_e32 v18, v22, v21
	s_nop 1
	v_mov_b32_dpp v19, v18 quad_perm:[1,0,3,2] row_mask:0xf bank_mask:0xf
	s_waitcnt lgkmcnt(0)
	v_add_f32_e32 v18, v18, v19
	s_nop 1
	v_mov_b32_dpp v19, v18 quad_perm:[2,3,0,1] row_mask:0xf bank_mask:0xf
	s_waitcnt lgkmcnt(0)
	v_add_f32_e32 v18, v18, v19
	s_nop 1
	v_mov_b32_dpp v19, v18 row_half_mirror row_mask:0xf bank_mask:0xf
	s_and_saveexec_b64 s[20:21], vcc
	s_cbranch_execz .LBB0_434
	s_waitcnt lgkmcnt(0)
	v_add_f32_e32 v18, v18, v19
	ds_write_b32 v118, v18 offset:672
.LBB0_434:
	s_or_b64 exec, exec, s[20:21]
	v_mul_f32_e32 v17, v17, v17
	v_mul_f32_e32 v9, v9, v9
	v_fmac_f32_e32 v17, v16, v16
	v_fmac_f32_e32 v9, v8, v8
	v_fmac_f32_e32 v17, v14, v14
	v_fmac_f32_e32 v9, v6, v6
	v_fmac_f32_e32 v17, v15, v15
	v_fmac_f32_e32 v9, v7, v7
	v_add_f32_e32 v6, v17, v9
	s_nop 1
	v_mov_b32_dpp v7, v6 quad_perm:[1,0,3,2] row_mask:0xf bank_mask:0xf
	s_waitcnt lgkmcnt(0)
	v_add_f32_e32 v6, v6, v7
	s_nop 1
	v_mov_b32_dpp v7, v6 quad_perm:[2,3,0,1] row_mask:0xf bank_mask:0xf
	s_waitcnt lgkmcnt(0)
	v_add_f32_e32 v6, v6, v7
	s_nop 1
	v_mov_b32_dpp v7, v6 row_half_mirror row_mask:0xf bank_mask:0xf
	s_and_saveexec_b64 s[20:21], vcc
	s_cbranch_execz .LBB0_436
	s_waitcnt lgkmcnt(0)
	v_add_f32_e32 v6, v6, v7
	ds_write_b32 v118, v6 offset:704
.LBB0_436:
	s_or_b64 exec, exec, s[20:21]
	v_mul_f32_e32 v6, v13, v13
	v_mul_f32_e32 v5, v5, v5
	v_fmac_f32_e32 v6, v12, v12
	v_fmac_f32_e32 v5, v4, v4
	v_fmac_f32_e32 v6, v10, v10
	v_fmac_f32_e32 v5, v2, v2
	v_fmac_f32_e32 v6, v11, v11
	v_fmac_f32_e32 v5, v3, v3
	v_add_f32_e32 v2, v6, v5
	s_nop 1
	v_mov_b32_dpp v3, v2 quad_perm:[1,0,3,2] row_mask:0xf bank_mask:0xf
	s_waitcnt lgkmcnt(0)
	v_add_f32_e32 v2, v2, v3
	s_nop 1
	v_mov_b32_dpp v3, v2 quad_perm:[2,3,0,1] row_mask:0xf bank_mask:0xf
	s_waitcnt lgkmcnt(0)
	v_add_f32_e32 v2, v2, v3
	s_nop 1
	v_mov_b32_dpp v3, v2 row_half_mirror row_mask:0xf bank_mask:0xf
	s_and_saveexec_b64 s[20:21], vcc
	s_cbranch_execz .LBB0_438
	s_waitcnt lgkmcnt(0)
	v_add_f32_e32 v2, v2, v3
	ds_write_b32 v118, v2 offset:736
